# weight conversion relocation sized to per-CU bandwidth: IN[l+1] converted by the 64 idle workgroups of the small-GEMM phase, OUT/XQ/XO[l+1] by the idle w_in-GEMM workgroups after w_down (layers 2,3 on
# speedup vs baseline: 1.0135x; 1.0060x over previous
; __device__ __forceinline__ int bid_fresh() { int t = blockIdx.x; asm volatile("" : "+s"(t)); return t; }
; __device__ __forceinline__ void phase0(PP p, unsigned char* shm) {
;     ...
;     for (int it = bid_fresh(); it < DEPTH * C_LAYER; it += gridDim.x) {
;         const int l = it / C_LAYER; int r = it % C_LAYER;
;         if (r < C_IN) { tconv_tile_w(p->in[5] + (size_t)l * D * INW, INW, r / 14, r % 14, (bf16_t*)(ws + WS_WIN) + (size_t)l * INW * D, D, tile, p->in[4] + (size_t)l * D); continue; } r -= C_IN;
;         if (r < C_OUT) { tconv_tile_w(p->in[23] + (size_t)l * D * D, D, r / 8, r % 8, (bf16_t*)(ws + WS_WOUT) + (size_t)l * D * D, D, tile, p->in[22] + (size_t)l * D); continue; } r -= C_OUT;
;         if (r < C_XQ) { tconv_tile_w(p->in[25] + (size_t)l * D * 512, 512, r / 2, r % 2, (bf16_t*)(ws + WS_WXQ) + (size_t)l * 512 * D, D, tile, p->in[24] + (size_t)l * D); continue; } r -= C_XQ;
;         if (r < C_XQ) { tconv_tile_w(p->in[26] + (size_t)l * D * 512, 512, r / 2, r % 2, (bf16_t*)(ws + WS_WKV) + (size_t)(l * 1024) * D, D, tile); continue; } r -= C_XQ;
;         if (r < C_XQ) { tconv_tile_w(p->in[27] + (size_t)l * D * 512, 512, r / 2, r % 2, (bf16_t*)(ws + WS_WKV) + (size_t)(l * 1024 + 512) * D, D, tile); continue; } r -= C_XQ;
;         if (r < C_XO) { tconv_tile_w(p->in[28] + (size_t)l * 512 * D, D, r / 8, r % 8, (bf16_t*)(ws + WS_WXO) + (size_t)l * D * 512, 512, tile); continue; } r -= C_XO;
;         if (r < C_UP) { tconv_tile_w(p->in[30] + (size_t)l * D * DFF, DFF, r / 32, r % 32, (bf16_t*)(ws + WS_WUP) + (size_t)l * DFF * D, D, tile, p->in[29] + (size_t)l * D); continue; } r -= C_UP;
;         if (r < C_DN) { if (l == 0) tconv_tile_w(p->in[31] + (size_t)l * DFF * D, D, r / 8, r % 8, (bf16_t*)(ws + WS_WDN) + (size_t)l * D * DFF, DFF, tile); continue; } r -= C_DN;
.LBB0_17:
	s_mov_b64 s[14:15], s[0:1]
	s_load_dwordx2 s[12:13], s[14:15], 0x110
	v_writelane_b32 v254, s26, 2
	s_cmpk_gt_i32 s26, 0x2fbf
	s_cbranch_scc1 .LBB0_71
	s_mov_b32 s27, 0
	s_mov_b32 s28, 0
	s_mov_b32 s29, s26
	s_mov_b32 s63, s66
	s_mov_b32 s64, 0
	s_mov_b32 s65, 4
	s_mov_b32 s84, 0x2763ff
	v_writelane_b32 v255, 0, 62

; __device__ __forceinline__ int bid_fresh() { int t = blockIdx.x; asm volatile("" : "+s"(t)); return t; }
; __device__ __forceinline__ void phase0(PP p, unsigned char* shm) {
;     ...
;     for (int it = bid_fresh(); it < DEPTH * C_LAYER; it += gridDim.x) {
;         const int l = it / C_LAYER; int r = it % C_LAYER;
;         if (r < C_IN) { tconv_tile_w(p->in[5] + (size_t)l * D * INW, INW, r / 14, r % 14, (bf16_t*)(ws + WS_WIN) + (size_t)l * INW * D, D, tile, p->in[4] + (size_t)l * D); continue; } r -= C_IN;
;         if (r < C_OUT) { tconv_tile_w(p->in[23] + (size_t)l * D * D, D, r / 8, r % 8, (bf16_t*)(ws + WS_WOUT) + (size_t)l * D * D, D, tile, p->in[22] + (size_t)l * D); continue; } r -= C_OUT;
;         if (r < C_XQ) { tconv_tile_w(p->in[25] + (size_t)l * D * 512, 512, r / 2, r % 2, (bf16_t*)(ws + WS_WXQ) + (size_t)l * 512 * D, D, tile, p->in[24] + (size_t)l * D); continue; } r -= C_XQ;
;         if (r < C_XQ) { tconv_tile_w(p->in[26] + (size_t)l * D * 512, 512, r / 2, r % 2, (bf16_t*)(ws + WS_WKV) + (size_t)(l * 1024) * D, D, tile); continue; } r -= C_XQ;
;         if (r < C_XQ) { tconv_tile_w(p->in[27] + (size_t)l * D * 512, 512, r / 2, r % 2, (bf16_t*)(ws + WS_WKV) + (size_t)(l * 1024 + 512) * D, D, tile); continue; } r -= C_XQ;
;         if (r < C_XO) { tconv_tile_w(p->in[28] + (size_t)l * 512 * D, D, r / 8, r % 8, (bf16_t*)(ws + WS_WXO) + (size_t)l * D * 512, 512, tile); continue; } r -= C_XO;
;         if (r < C_UP) { tconv_tile_w(p->in[30] + (size_t)l * D * DFF, DFF, r / 32, r % 32, (bf16_t*)(ws + WS_WUP) + (size_t)l * DFF * D, D, tile, p->in[29] + (size_t)l * D); continue; } r -= C_UP;
;         if (r < C_DN) { if (l == 0) tconv_tile_w(p->in[31] + (size_t)l * DFF * D, D, r / 8, r % 8, (bf16_t*)(ws + WS_WDN) + (size_t)l * D * DFF, DFF, tile); continue; } r -= C_DN;
;         bf16_t* wsm = (bf16_t*)(ws + WS_WSM) + (size_t)l * 1536 * 512;
;         if (r < C_GLU) { tconv_tile_w(p->in[14] + (size_t)l * 512 * 512, 512, r / 2, r % 2, wsm, 512, tile); continue; } r -= C_GLU;
;         if (r < C_POOL) { const int gi = r >> 2, q = r & 3; tconv_tile(p->in[15] + (size_t)(l * 4 + gi) * 128 * 128, 128, q >> 1, q & 1, wsm + (size_t)(512 + gi * 128) * 512 + gi * 128, 512, tile); continue; } r -= C_POOL;
;         tconv_tile_w(p->in[21] + (size_t)l * 512 * 512, 512, r / 2, r % 2, wsm + (size_t)1024 * 512, 512, tile);
;     }
.Ltc_exit_1:
	s_waitcnt vmcnt(0) lgkmcnt(0)
	s_barrier
	v_readlane_b32 s2, v255, 62
	s_nop 3
	s_cmp_eq_u32 s2, 0
	s_cbranch_scc1 .Ltc_ret0
	s_cmp_eq_u32 s2, 1
	s_cbranch_scc1 .Ltc_ret1
	s_branch .Ltc_ret2

; __device__ __forceinline__ int bid_fresh() { int t = blockIdx.x; asm volatile("" : "+s"(t)); return t; }
; __global__ void __launch_bounds__(512, 2) hymba_fwd(Params p_unused) {
;     ...
;           { const int G = (int)gridDim.x, c = (int)bid_fresh(), nfull = 448 % G, nidle = (nfull == 0) ? 0 : G - nfull;
;             if (nidle > 0 && c >= nfull) { for (int r = c - nfull; r < 1024; r += nidle)
;                 tconv_tile_w(p->in[31] + (size_t)l * DFF * D, D, r / 8, r % 8, (bf16_t*)(ws + WS_WDN) + (size_t)l * D * DFF, DFF, (float*)shm); }
;             else if (nidle == 0) { for (int r = c; r < 1024; r += G) tconv_tile_w(p->in[31] + (size_t)l * DFF * D, D, r / 8, r % 8, (bf16_t*)(ws + WS_WDN) + (size_t)l * D * DFF, DFF, (float*)shm); } } }
.LBB0_286:
	s_mov_b32 s12, s30
	v_readlane_b32 s2, v254, 52
	s_cmp_lt_i32 s12, s2
	v_readlane_b32 s16, v254, 49
	s_cselect_b64 s[2:3], -1, 0
	v_readlane_b32 s17, v254, 50
	s_or_b64 s[16:17], s[2:3], s[16:17]
	s_mov_b64 s[2:3], -1
	s_and_b64 vcc, exec, s[16:17]
	s_cbranch_vccnz .LBB0_291
	v_readlane_b32 s2, v254, 52
	s_sub_i32 s2, s12, s2
	s_cmpk_gt_i32 s2, 0x3ff
	v_readlane_b32 s24, v255, 17
	v_readlane_b32 s25, v254, 54
	s_movk_i32 s34, 0x404
	s_cbranch_scc1 .LBB0_290
	s_waitcnt lgkmcnt(0)
	v_writelane_b32 v124, s2, 0
	v_writelane_b32 v124, s3, 1
	v_writelane_b32 v124, s4, 2
	v_writelane_b32 v124, s5, 3
	v_writelane_b32 v124, s6, 4
	v_writelane_b32 v124, s7, 5
	v_writelane_b32 v124, s12, 6
	v_writelane_b32 v124, s13, 7
	v_writelane_b32 v124, s14, 8
	v_writelane_b32 v124, s15, 9
	v_writelane_b32 v124, s27, 10
	v_writelane_b32 v124, s28, 11
	v_writelane_b32 v124, s29, 12
	v_writelane_b32 v124, s30, 13
	v_writelane_b32 v124, s31, 14
	v_writelane_b32 v124, s33, 15
	v_writelane_b32 v124, s34, 16
	v_writelane_b32 v124, s35, 17
	v_writelane_b32 v124, s36, 18
	v_writelane_b32 v124, s37, 19
	v_writelane_b32 v124, s38, 20
	v_writelane_b32 v124, s39, 21
	v_writelane_b32 v124, s40, 22
	v_writelane_b32 v124, s41, 23
	v_writelane_b32 v124, s42, 24
	v_writelane_b32 v124, s43, 25
	v_writelane_b32 v124, s44, 26
	v_writelane_b32 v124, s45, 27
	v_writelane_b32 v124, s46, 28
	v_writelane_b32 v124, s47, 29
	v_writelane_b32 v124, s48, 30
	v_writelane_b32 v124, s49, 31
	v_writelane_b32 v124, s50, 32
	v_writelane_b32 v124, s51, 33
	v_writelane_b32 v124, s52, 34
	v_writelane_b32 v124, s53, 35
	v_writelane_b32 v124, s54, 36
	v_writelane_b32 v124, s55, 37
	v_writelane_b32 v124, s56, 38
	v_writelane_b32 v124, s57, 39
	v_writelane_b32 v124, s58, 40
	v_writelane_b32 v124, s59, 41
	v_writelane_b32 v124, s60, 42
	v_writelane_b32 v124, s61, 43
	v_writelane_b32 v124, s62, 44
	v_writelane_b32 v124, s63, 45
	v_writelane_b32 v124, s64, 46
	v_writelane_b32 v124, s65, 47
	v_writelane_b32 v124, s68, 48
	v_writelane_b32 v124, s69, 49
	v_writelane_b32 v124, s70, 50
	v_writelane_b32 v124, s71, 51
	v_writelane_b32 v124, s72, 52
	v_writelane_b32 v124, s73, 53
	v_writelane_b32 v124, s74, 54
	v_writelane_b32 v124, s75, 55
	v_writelane_b32 v124, s76, 56
	v_writelane_b32 v124, s77, 57
	v_writelane_b32 v124, s78, 58
	v_writelane_b32 v124, s79, 59
	v_writelane_b32 v124, s80, 60
	v_writelane_b32 v124, s81, 61
	v_writelane_b32 v124, s82, 62
	v_writelane_b32 v124, s83, 63
	v_writelane_b32 v125, s84, 0
	s_mov_b32 s84, 0x89800
	v_readlane_b32 s29, v254, 2
	v_readlane_b32 s3, v254, 52
	v_readlane_b32 s63, v255, 17
	v_readlane_b32 s27, v255, 20
	s_mov_b64 s[14:15], s[0:1]
	s_load_dwordx2 s[12:13], s[0:1], 0x110
	s_nop 3
	s_sub_u32 s29, s29, s3
	s_mov_b32 s64, s27
	s_add_u32 s65, s27, 2
	s_min_u32 s65, s65, 4
	s_add_u32 s27, s27, 0
	s_mov_b32 s28, 9
	v_writelane_b32 v255, 1, 62
	s_branch .Ltc_entry

; __device__ __forceinline__ int bid_fresh() { int t = blockIdx.x; asm volatile("" : "+s"(t)); return t; }
; __global__ void __launch_bounds__(512, 2) hymba_fwd(Params p_unused) {
;     ...
;           { const int G = (int)gridDim.x, c = (int)bid_fresh(), nfull = 448 % G, nidle = (nfull == 0) ? 0 : G - nfull;
;             if (nidle > 0 && c >= nfull) { for (int r = c - nfull; r < 1024; r += nidle)
;                 tconv_tile_w(p->in[31] + (size_t)l * DFF * D, D, r / 8, r % 8, (bf16_t*)(ws + WS_WDN) + (size_t)l * D * DFF, DFF, (float*)shm); }
;             else if (nidle == 0) { for (int r = c; r < 1024; r += G) tconv_tile_w(p->in[31] + (size_t)l * DFF * D, D, r / 8, r % 8, (bf16_t*)(ws + WS_WDN) + (size_t)l * D * DFF, DFF, (float*)shm); } } }
.Ltc_skipcall_1:
.LBB0_290:
	s_mov_b64 s[2:3], 0

; #define GSYNC() do { for (int _r = 0; _r < SYNC_REPS; ++_r) xcd_barrier(xbar); } while (0)
; __device__ __forceinline__ PP get_pp() { PP q = (PP)__builtin_amdgcn_kernarg_segment_ptr(); asm volatile("" : "+s"(q)); return q; }
; __device__ __forceinline__ int bid_fresh() { int t = blockIdx.x; asm volatile("" : "+s"(t)); return t; }
; #define PG8_LAS __attribute__((address_space(3)))
; __global__ void __launch_bounds__(512, 2) hymba_fwd(Params p_unused) {
;     ...
;         { PP p = get_pp(); unsigned char* ws = p->ws;
;           pg8::SmallOrder S{(int)gridDim.x, (int)bid_fresh()};
;           pg8::Gemm g{(const bf16_t*)(ws + WS_GPH), (const bf16_t*)(ws + WS_WSM) + (size_t)l * 1536 * 512, T, 1536, 512, 512};
;           pg8::EpiSmall E{(bf16_t*)(ws + WS_YN), (const bf16_t*)(ws + WS_GPH), p->in[16] + (size_t)l * 512, (float*)(ws + WS_SSG)};
;           pg8::gemm_phase<pg8::EpiSmall, pg8::SmallOrder>((PG8_LAS unsigned char*)shm, g, S, E); }
;         GSYNC();
.LBB0_916:
	s_waitcnt vmcnt(0)
	v_readlane_b32 s30, v254, 2
	s_barrier
	s_branch .LBB0_917
.Ltc_p4_idle:
	s_waitcnt lgkmcnt(0)
	v_readlane_b32 s2, v255, 20
	s_nop 3
	s_cmp_ge_u32 s2, 3
	s_cbranch_scc1 .Ltc_skipcall_2
	s_cmp_eq_u32 s2, 0
	s_cbranch_scc1 .Ltc_skipcall_2
	v_writelane_b32 v124, s2, 0
	v_writelane_b32 v124, s3, 1
	v_writelane_b32 v124, s4, 2
	v_writelane_b32 v124, s5, 3
	v_writelane_b32 v124, s6, 4
	v_writelane_b32 v124, s7, 5
	v_writelane_b32 v124, s12, 6
	v_writelane_b32 v124, s13, 7
	v_writelane_b32 v124, s14, 8
	v_writelane_b32 v124, s15, 9
	v_writelane_b32 v124, s27, 10
	v_writelane_b32 v124, s28, 11
	v_writelane_b32 v124, s29, 12
	v_writelane_b32 v124, s30, 13
	v_writelane_b32 v124, s31, 14
	v_writelane_b32 v124, s33, 15
	v_writelane_b32 v124, s34, 16
	v_writelane_b32 v124, s35, 17
	v_writelane_b32 v124, s36, 18
	v_writelane_b32 v124, s37, 19
	v_writelane_b32 v124, s38, 20
	v_writelane_b32 v124, s39, 21
	v_writelane_b32 v124, s40, 22
	v_writelane_b32 v124, s41, 23
	v_writelane_b32 v124, s42, 24
	v_writelane_b32 v124, s43, 25
	v_writelane_b32 v124, s44, 26
	v_writelane_b32 v124, s45, 27
	v_writelane_b32 v124, s46, 28
	v_writelane_b32 v124, s47, 29
	v_writelane_b32 v124, s48, 30
	v_writelane_b32 v124, s49, 31
	v_writelane_b32 v124, s50, 32
	v_writelane_b32 v124, s51, 33
	v_writelane_b32 v124, s52, 34
	v_writelane_b32 v124, s53, 35
	v_writelane_b32 v124, s54, 36
	v_writelane_b32 v124, s55, 37
	v_writelane_b32 v124, s56, 38
	v_writelane_b32 v124, s57, 39
	v_writelane_b32 v124, s58, 40
	v_writelane_b32 v124, s59, 41
	v_writelane_b32 v124, s60, 42
	v_writelane_b32 v124, s61, 43
	v_writelane_b32 v124, s62, 44
	v_writelane_b32 v124, s63, 45
	v_writelane_b32 v124, s64, 46
	v_writelane_b32 v124, s65, 47
	v_writelane_b32 v124, s68, 48
	v_writelane_b32 v124, s69, 49
	v_writelane_b32 v124, s70, 50
	v_writelane_b32 v124, s71, 51
	v_writelane_b32 v124, s72, 52
	v_writelane_b32 v124, s73, 53
	v_writelane_b32 v124, s74, 54
	v_writelane_b32 v124, s75, 55
	v_writelane_b32 v124, s76, 56
	v_writelane_b32 v124, s77, 57
	v_writelane_b32 v124, s78, 58
	v_writelane_b32 v124, s79, 59
	v_writelane_b32 v124, s80, 60
	v_writelane_b32 v124, s81, 61
	v_writelane_b32 v124, s82, 62
	v_writelane_b32 v124, s83, 63
	v_writelane_b32 v125, s84, 0
	s_mov_b32 s84, 0x400
	v_readlane_b32 s29, v254, 2
	v_readlane_b32 s27, v255, 20
	s_mov_b64 s[14:15], s[0:1]
	s_load_dwordx2 s[12:13], s[0:1], 0x110
	s_nop 3
	s_sub_u32 s29, s29, 192
	s_mov_b32 s63, 64
	s_mov_b32 s64, s27
	s_add_u32 s65, s27, 2
	s_min_u32 s65, s65, 4
	s_add_u32 s27, s27, 1
	s_mov_b32 s28, 0
	v_writelane_b32 v255, 2, 62
	s_branch .Ltc_entry

; __device__ __forceinline__ void xcd_barrier(const XcdBarrier& b) {
;     asm volatile("s_waitcnt vmcnt(0)" ::: "memory");
;     __syncthreads();
;     if (threadIdx.x == 0) {
;         unsigned* bar = b.bar;
;         __builtin_amdgcn_s_waitcnt(0);
;         unsigned nloc = b.st[0], nx = b.st[1];
;         if (nloc == 0u) { xcd_barrier_complete(bar, b.x, nloc, nx); b.st[0] = nloc; b.st[1] = nx; }
.Ltc_skipcall_2:
.LBB0_917:
	s_waitcnt vmcnt(0)
	s_waitcnt lgkmcnt(0)
	s_barrier
	s_mov_b64 s[8:9], exec
	v_readlane_b32 s2, v254, 0
	v_readlane_b32 s3, v254, 1
	s_and_b64 s[2:3], s[8:9], s[2:3]
	s_mov_b64 exec, s[2:3]
	s_cbranch_execz .LBB0_969
	v_readlane_b32 s2, v254, 59
	s_waitcnt vmcnt(0) expcnt(0) lgkmcnt(0)
	s_nop 0
	v_mov_b32_e32 v0, s2
	ds_read_b32 v3, v0
	v_readlane_b32 s2, v254, 60
	s_waitcnt lgkmcnt(0)
	v_cmp_ne_u32_e32 vcc, 0, v3
	v_mov_b32_e32 v0, s2
	ds_read_b32 v2, v0
	s_cbranch_vccnz .LBB0_933
	s_mov_b32 s14, 1
	s_branch .LBB0_921
